# attention phase: XCDs de-phased by s_sleep (blockIdx%8 x 1.3us) to flatten HBM demand
# baseline (speedup 1.0000x reference)
; #define LAS __attribute__((address_space(3)))
; #define SYNC(k) do { if ((k) + 1 < hi) { if (lo < 0) grid.sync(); else xcd_barrier(bar); } } while (0)
; __device__ __forceinline__ void p3_attention(const Args& a, LAS unsigned char* lds) {
;     const int tid = threadIdx.x, lane = tid & 63, w = tid >> 6, l15 = lane & 15, q4 = lane >> 4;
;     const bf16_t* QKVA = (const bf16_t*)(a.ws + WS_QKVA);
;     bf16_t* OG = (bf16_t*)((unsigned char*)a.out + OUT_OG); float* LSE = (float*)((unsigned char*)a.out + OUT_LSE);
;     LAS bf16_t* Qs = (LAS bf16_t*)(lds + ATT_Q); LAS bf16_t* Ks = (LAS bf16_t*)(lds + ATT_K); LAS bf16_t* Vt = (LAS bf16_t*)(lds + ATT_V);
;     const int G = gridDim.x, bx = blockIdx.x;
;     const int vcu = (G % 8 == 0) ? (bx % 8) * (G / 8) + bx / 8 : bx;
;     u32x4 rq[4], rk[6], rv[6];
;     int item = vcu;
;     if (item < ATT_ITEMS) { const AttItem it = att_decode(item); att_load(QKVA, it, tid, rq, rk, rv); }
; __global__ void __launch_bounds__(NTHR, 2) mega(Args a) {
;     ...
;     if (IN(0)) { p0_prologue(a, lds); SYNC(0); }
;     if (IN(1)) { p1_prenorm(a); SYNC(1); }
;     if (IN(2)) { Epi<EP_QKV> E{(bf16_t*)(ws + WS_QKVA), 4608, nullptr, nullptr, nullptr, nullptr, nullptr, nullptr};
;                  run_gemm<EP_QKV>(lds, (const bf16_t*)(ws + WS_HB), (const bf16_t*)(ws + WS_WA), 4608, 1024, E); SYNC(2); }
;     if (IN(3)) { p3_attention(a, lds); SYNC(3); }
.LBB0_565:
.LBB0_566:
	s_cmp_lt_i32 s94, 4
	s_cselect_b64 s[0:1], -1, 0
	s_cmp_gt_i32 s95, 3
	s_cselect_b64 s[2:3], -1, 0
	s_and_b64 s[0:1], s[0:1], s[2:3]
	s_andn2_b64 vcc, exec, s[0:1]
	s_cbranch_vccnz .LBB0_674
	s_and_b32 s98, s89, 7
	s_cmp_eq_u32 s98, 0
	s_cbranch_scc1 .Latt_nodelay
.Latt_delay:
	s_sleep 48
	s_add_i32 s98, s98, -1
	s_cmp_lg_u32 s98, 0
	s_cbranch_scc1 .Latt_delay
.Latt_nodelay:
	s_and_b32 s0, s84, 7
	s_cmp_lg_u32 s0, 0
	s_mov_b32 s23, s89
	s_cbranch_scc1 .LBB0_569
	s_ashr_i32 s1, s89, 31
	s_lshr_b32 s1, s1, 29
	s_add_i32 s1, s89, s1
	s_and_b32 s2, s1, -8
	s_ashr_i32 s0, s84, 3
	s_sub_i32 s2, s89, s2
	s_mul_i32 s0, s0, s2
	s_ashr_i32 s1, s1, 3
	s_add_i32 s23, s0, s1
